# XCD-group-local barriers at 16 of 20 phase seams (GLA/attn/pool units remapped to be group-local), purity-checked fast path
# speedup vs baseline: 1.0131x; 1.0131x over previous
; #define LAS __attribute__((address_space(3)))
; __device__ __forceinline__ unsigned xb_add(unsigned* p, unsigned v) { return __hip_atomic_fetch_add(p, v, __ATOMIC_RELAXED, __HIP_MEMORY_SCOPE_AGENT); }
; __device__ __forceinline__ unsigned xb_xcc_id() { return (unsigned)__builtin_amdgcn_s_getreg((3 << 11) | 20) & 0xFu; }
; __device__ __forceinline__ XcdBarrier xcd_barrier_post(unsigned* bar, volatile LAS unsigned* st) {
;     XcdBarrier b; b.bar = bar; b.x = xb_xcc_id(); b.st = st;
;     if (threadIdx.x == 0) (void)xb_add(&bar[XB_XCNT(b.x)], 1u);
;     return b;
; __global__ void __launch_bounds__(NTHREADS, 2) fwd_kernel(Args a) {
;     ...
;     const int G = gridDim.x, wg = blockIdx.x;
;     unsigned char* ws = a.ws;
;     float* ssqA = (float*)(ws + WS_SSQ); float* ssqB = (float*)(ws + WS_SSQ1);
;     bf16_t* XB = (bf16_t*)(ws + WS_XB); bf16_t* O2 = (bf16_t*)(ws + WS_O2); bf16_t* BIG = (bf16_t*)(ws + WS_BIG);
;     const int lo = a.ph_lo, hi = a.ph_hi;
;     int pid = 0;
;     if (threadIdx.x < 16) ((LAS unsigned*)(lds + LDS_BARST))[threadIdx.x] = 0u;
;     __syncthreads();
;     if (lo > hi) grid.sync();
;     XcdBarrier bar = xcd_barrier_post((unsigned*)(ws + WS_BAR), (volatile LAS unsigned*)(lds + LDS_BARST));
.LBB0_14:
	s_load_dwordx16 s[4:19], s[0:1], 0x0
	s_add_u32 s86, s24, 0x310000
	s_addc_u32 s87, s25, 0
	s_waitcnt lgkmcnt(0)
	v_writelane_b32 v252, s4, 0
	s_nop 1
	v_writelane_b32 v252, s5, 1
	v_writelane_b32 v252, s6, 2
	v_writelane_b32 v252, s7, 3
	v_writelane_b32 v252, s8, 4
	v_writelane_b32 v252, s9, 5
	v_writelane_b32 v252, s10, 6
	v_writelane_b32 v252, s11, 7
	v_writelane_b32 v252, s12, 8
	v_writelane_b32 v252, s13, 9
	v_writelane_b32 v252, s14, 10
	v_writelane_b32 v252, s15, 11
	v_writelane_b32 v252, s16, 12
	v_writelane_b32 v252, s17, 13
	v_writelane_b32 v252, s18, 14
	v_writelane_b32 v252, s19, 15
	s_load_dwordx16 s[4:19], s[0:1], 0x40
	s_getreg_b32 s0, hwreg(HW_REG_XCC_ID, 0, 4)
	s_and_b32 s68, s0, 15
	s_waitcnt lgkmcnt(0)
	v_writelane_b32 v252, s4, 16
	s_nop 1
	v_writelane_b32 v252, s5, 17
	v_writelane_b32 v252, s6, 18
	v_writelane_b32 v252, s7, 19
	v_writelane_b32 v252, s8, 20
	v_writelane_b32 v252, s9, 21
	v_writelane_b32 v252, s10, 22
	v_writelane_b32 v252, s11, 23
	v_writelane_b32 v252, s12, 24
	v_writelane_b32 v252, s13, 25
	v_writelane_b32 v252, s14, 26
	v_writelane_b32 v252, s15, 27
	v_writelane_b32 v252, s16, 28
	v_writelane_b32 v252, s17, 29
	v_writelane_b32 v252, s18, 30
	v_writelane_b32 v252, s19, 31
	v_cmp_eq_u32_e64 s[4:5], 0, v210
	s_mov_b64 s[0:1], exec
	s_nop 0
	v_writelane_b32 v252, s4, 32
	s_nop 1
	v_writelane_b32 v252, s5, 33
	s_and_b64 s[4:5], s[0:1], s[4:5]
	s_mov_b64 exec, s[4:5]
	s_cbranch_execz .LBB0_17
	s_mov_b64 s[4:5], exec
	v_mbcnt_lo_u32_b32 v0, s4, 0
	v_mbcnt_hi_u32_b32 v0, s5, v0
	v_cmp_eq_u32_e32 vcc, 0, v0
	s_and_b64 s[6:7], exec, vcc
	s_mov_b64 exec, s[6:7]
	s_cbranch_execz .LBB0_17
	s_lshl_b32 s3, s68, 8
	s_bcnt1_i32_b64 s4, s[4:5]
	v_mov_b32_e32 v0, s3
	v_mov_b32_e32 v1, s4
	global_atomic_add v0, v1, s[86:87] offset:1024
	s_and_b32 s3, s2, 7
	s_lshl_b32 s3, s3, 7
	s_addk_i32 s3, 0x3c00
	s_lshl_b32 s4, 1, s68
	v_mov_b32_e32 v2, s3
	v_mov_b32_e32 v3, s4
	global_atomic_or v2, v3, s[86:87]

; __device__ __forceinline__ unsigned xb_ld(unsigned* p)              { return __hip_atomic_load(p, __ATOMIC_RELAXED, __HIP_MEMORY_SCOPE_AGENT); }
; __device__ __forceinline__ unsigned xb_add(unsigned* p, unsigned v) { return __hip_atomic_fetch_add(p, v, __ATOMIC_RELAXED, __HIP_MEMORY_SCOPE_AGENT); }
; #define XB_SPIN(cond, bar) do { unsigned _sp = 0; while (cond) { __builtin_amdgcn_s_sleep(1); \
;     if ((++_sp & 255u) == 0u) { if (xb_ld(&(bar)[XB_TMO])) break; if (_sp > XB_SPIN_CAP) { atomicAdd(&(bar)[XB_TMO], 1u); break; } } } } while (0)
; __device__ __forceinline__ void xcd_barrier(const XcdBarrier& b) {
;     asm volatile("s_waitcnt vmcnt(0)" ::: "memory");
;     __syncthreads();
;     if (threadIdx.x == 0) {
;         unsigned* bar = b.bar;
;         __builtin_amdgcn_s_waitcnt(0);
;         unsigned nloc = b.st[0], nx = b.st[1];
;         if (nloc == 0u) { xcd_barrier_complete(bar, b.x, nloc, nx); b.st[0] = nloc; b.st[1] = nx; }
;         const unsigned old = xb_add(&bar[XB_XSUB(b.x)], 1u);
;         const unsigned gen = old / nloc;
;         if (old + 1u == (gen + 1u) * nloc) {
;             __builtin_amdgcn_fence(__ATOMIC_RELEASE, "agent");
;             asm volatile("s_waitcnt vmcnt(0)" ::: "memory");
;             const unsigned og = xb_add(&bar[XB_TOP], 1u);
;             const unsigned tg = og / nx;
;             if (og + 1u == (tg + 1u) * nx) xb_add(&bar[XB_TOPGEN], 1u);
;             else XB_SPIN(xb_ld(&bar[XB_TOPGEN]) == tg, bar);
;             __builtin_amdgcn_fence(__ATOMIC_ACQUIRE, "agent");
;             xb_add(&bar[XB_XGEN(b.x)], 1u);
;             asm volatile("s_waitcnt vmcnt(0)" ::: "memory");
;         } else {
;             XB_SPIN(xb_ld(&bar[XB_XGEN(b.x)]) == gen, bar);
;             __builtin_amdgcn_fence(__ATOMIC_ACQUIRE, "agent");
;             asm volatile("s_waitcnt vmcnt(0)" ::: "memory");
;         }
.LBB0_1112:
	v_readlane_b32 s68, v252, 0
	v_readlane_b32 s69, v252, 1
	v_readlane_b32 s78, v252, 10
	v_readlane_b32 s79, v252, 11
	v_readlane_b32 s80, v252, 12
	v_readlane_b32 s81, v252, 13
	s_add_i32 s0, s86, 1
	v_readlane_b32 s68, v255, 0
	v_readlane_b32 s78, v255, 2
	v_readlane_b32 s80, v255, 4
	v_readlane_b32 s64, v255, 6
	s_cmp_ge_i32 s0, s27
	s_mov_b64 s[46:47], 0
	v_readlane_b32 s70, v252, 2
	v_readlane_b32 s71, v252, 3
	v_readlane_b32 s72, v252, 4
	v_readlane_b32 s73, v252, 5
	v_readlane_b32 s74, v252, 6
	v_readlane_b32 s75, v252, 7
	v_readlane_b32 s76, v252, 8
	v_readlane_b32 s77, v252, 9
	v_readlane_b32 s82, v252, 14
	v_readlane_b32 s83, v252, 15
	v_readlane_b32 s69, v255, 1
	v_readlane_b32 s79, v255, 3
	v_readlane_b32 s81, v255, 5
	v_readlane_b32 s65, v255, 7
	s_mov_b32 s63, 0x10000
	s_mov_b32 s93, 0x8800
	s_mov_b64 s[94:95], 0x1000
	s_cbranch_scc1 .LBB0_1166
	s_waitcnt vmcnt(0)
	s_waitcnt lgkmcnt(0)
	s_barrier
	s_mov_b64 s[0:1], exec
	v_readlane_b32 s8, v252, 32
	v_readlane_b32 s9, v252, 33
	v_readlane_b32 s44, v252, 46
	s_and_b64 s[8:9], s[0:1], s[8:9]
	v_readlane_b32 s45, v252, 47
	s_mov_b64 exec, s[8:9]
	s_cbranch_execz .LBB0_1165
	v_mov_b32_e32 v0, 0x23fc8
	ds_read_b32 v1, v0
	s_waitcnt lgkmcnt(0)
	v_readfirstlane_b32 s40, v1
	s_cmp_lg_u32 s40, 0
	s_cbranch_scc1 .Lgb_have_flag
	s_add_u32 s38, s24, 0x313c00
	s_addc_u32 s39, s25, 0
	v_mov_b32_e32 v1, 0
	global_load_dword v2, v1, s[38:39] sc1
	global_load_dword v3, v1, s[38:39] offset:128 sc1
	global_load_dword v4, v1, s[38:39] offset:256 sc1
	global_load_dword v5, v1, s[38:39] offset:384 sc1
	s_waitcnt vmcnt(0)
	v_bcnt_u32_b32 v2, v2, 0
	v_bcnt_u32_b32 v3, v3, 0
	v_bcnt_u32_b32 v4, v4, 0
	v_bcnt_u32_b32 v5, v5, 0
	v_xor_b32_e32 v2, 1, v2
	v_xor_b32_e32 v3, 1, v3
	v_xor_b32_e32 v4, 1, v4
	v_xor_b32_e32 v5, 1, v5
	v_or3_b32 v0, v2, v3, v4
	v_or_b32_e32 v0, v0, v5
	global_load_dword v2, v1, s[38:39] offset:512 sc1
	global_load_dword v3, v1, s[38:39] offset:640 sc1
	global_load_dword v4, v1, s[38:39] offset:768 sc1
	global_load_dword v5, v1, s[38:39] offset:896 sc1
	s_waitcnt vmcnt(0)
	v_bcnt_u32_b32 v2, v2, 0
	v_bcnt_u32_b32 v3, v3, 0
	v_bcnt_u32_b32 v4, v4, 0
	v_bcnt_u32_b32 v5, v5, 0
	v_xor_b32_e32 v2, 1, v2
	v_xor_b32_e32 v3, 1, v3
	v_xor_b32_e32 v4, 1, v4
	v_xor_b32_e32 v5, 1, v5
	v_or3_b32 v2, v2, v3, v4
	v_or3_b32 v0, v0, v2, v5
	s_nop 1
	v_readfirstlane_b32 s40, v0
	s_cmp_eq_u32 s40, 0
	s_cselect_b32 s40, 1, 2
	s_cmp_eq_u32 s28, 0x100
	s_cselect_b32 s40, s40, 2
	v_mov_b32_e32 v0, 0x23fc8
	v_mov_b32_e32 v1, s40
	ds_write_b32 v0, v1
	s_waitcnt lgkmcnt(0)
.Lgb_have_flag:
	s_cmp_eq_u32 s40, 1
	s_cbranch_scc0 .Lgb_orig_g1
	s_and_b32 s40, s2, 7
	s_lshl_b32 s40, s40, 7
	s_add_u32 s38, s24, 0x313800
	s_addc_u32 s39, s25, 0
	v_mov_b32_e32 v0, s40
	v_mov_b32_e32 v1, 1
	global_atomic_add v2, v0, v1, s[38:39] sc0
	s_mov_b32 s40, 0
	s_waitcnt vmcnt(0)
	v_or_b32_e32 v2, 31, v2
	v_add_u32_e32 v2, 1, v2
.Lgb_spin_g1:
	global_load_dword v3, v0, s[38:39] sc1
	s_waitcnt vmcnt(0)
	v_sub_u32_e32 v3, v3, v2
	v_cmp_gt_i32_e32 vcc, 0, v3
	s_cbranch_vccz .Lgb_done_g1
	s_sleep 1
	s_add_i32 s40, s40, 1
	s_cmp_lt_u32 s40, 0x100000
	s_cbranch_scc1 .Lgb_spin_g1
.Lgb_done_g1:
	buffer_inv sc1
	s_waitcnt vmcnt(0)
	s_branch .LBB0_1165
.Lgb_orig_g1:
	v_readlane_b32 s8, v254, 56
	s_waitcnt vmcnt(0) expcnt(0) lgkmcnt(0)
	s_nop 0
	v_mov_b32_e32 v0, s8
	ds_read_b32 v2, v0
	v_readlane_b32 s8, v254, 57
	s_waitcnt lgkmcnt(0)
	v_cmp_ne_u32_e32 vcc, 0, v2
	v_mov_b32_e32 v0, s8
	ds_read_b32 v0, v0
	s_cbranch_vccnz .LBB0_1129
	s_mov_b32 s8, 1
	s_branch .LBB0_1117

; __device__ __forceinline__ float ssq_row(const float* part, int row) {
;     const f32x4* p = (const f32x4*)(part + (size_t)row * 16);
;     const f32x4 a = p[0], b = p[1], c = p[2], d = p[3];
;     return (((a[0] + a[1]) + (a[2] + a[3])) + ((b[0] + b[1]) + (b[2] + b[3]))) + (((c[0] + c[1]) + (c[2] + c[3])) + ((d[0] + d[1]) + (d[2] + d[3])));
; }
; __device__ __forceinline__ void pool_phase(LAS unsigned char* lds, const bf16_t* x, const float* ssq, const float* gain, bf16_t* Ag, int G, int wg) {
;     ...
;     for (int u = wg; u < NB * 32; u += G) {
;         const int b = u >> 5, t0 = (u & 31) * 64; const size_t rb = (size_t)b * SEQ;
;         __syncthreads();
;         if (tid < 80) { const int t = t0 - 16 + tid; rs[tid] = (t >= 0) ? __builtin_amdgcn_rsqf(pg8::ssq_row(ssq, (int)(rb + t)) * (1.f / 1024.f) + EPS) : 0.f; }
.LBB0_1173:
	s_and_b32 s0, s9, 7
	s_lshl_b32 s0, s0, 6
	s_lshr_b32 s1, s9, 8
	s_lshl_b32 s1, s1, 5
	s_or_b32 s0, s0, s1
	s_bfe_u32 s1, s9, 0x50003
	s_or_b32 s0, s0, s1
	s_lshl_b32 s16, s0, 6
	s_and_b32 s16, s16, 0x7c0
	s_ashr_i32 s0, s0, 5
	s_ashr_i32 s1, s0, 31
	s_lshl_b64 s[48:49], s[0:1], 11
	s_barrier
	s_and_saveexec_b64 s[0:1], s[40:41]
	s_cbranch_execz .LBB0_1177
	v_add_u32_e32 v14, s16, v102
	v_cmp_lt_i32_e32 vcc, -1, v14
	v_mov_b32_e32 v5, 0
	s_and_saveexec_b64 s[38:39], vcc
	s_cbranch_execz .LBB0_1176
	v_add_u32_e32 v14, s48, v14
	v_ashrrev_i32_e32 v15, 31, v14
	v_lshlrev_b64 v[14:15], 6, v[14:15]
	v_lshl_add_u64 v[26:27], s[24:25], 0, v[14:15]
	global_load_dwordx4 v[14:17], v[26:27], off
	global_load_dwordx4 v[18:21], v[26:27], off offset:32
	global_load_dwordx4 v[22:25], v[26:27], off offset:16
	s_nop 0
	global_load_dwordx4 v[26:29], v[26:27], off offset:48
	s_waitcnt vmcnt(3)
	v_mov_b32_e32 v30, v14
	s_waitcnt vmcnt(2)
	v_mov_b32_e32 v31, v18
	v_mov_b32_e32 v18, v15
	v_mov_b32_e32 v14, v16
	v_mov_b32_e32 v15, v20
	v_mov_b32_e32 v20, v17
	s_waitcnt vmcnt(1)
	v_mov_b32_e32 v16, v22
	s_waitcnt vmcnt(0)
	v_mov_b32_e32 v17, v26
	v_mov_b32_e32 v26, v23
	v_mov_b32_e32 v22, v24
	v_mov_b32_e32 v23, v28
	v_mov_b32_e32 v28, v25
	v_pk_add_f32 v[18:19], v[30:31], v[18:19]
	v_pk_add_f32 v[14:15], v[14:15], v[20:21]
	v_pk_add_f32 v[16:17], v[16:17], v[26:27]
	v_pk_add_f32 v[20:21], v[22:23], v[28:29]
	v_pk_add_f32 v[14:15], v[18:19], v[14:15]
	v_pk_add_f32 v[16:17], v[16:17], v[20:21]
	s_nop 0
	v_pk_add_f32 v[14:15], v[14:15], v[16:17]
	s_nop 0
	v_add_f32_e32 v5, v14, v15
	v_fmamk_f32 v5, v5, 0x3a800000, v211
	v_rsq_f32_e32 v5, v5

; __device__ __forceinline__ unsigned xb_add(unsigned* p, unsigned v) { return __hip_atomic_fetch_add(p, v, __ATOMIC_RELAXED, __HIP_MEMORY_SCOPE_AGENT); }
; __device__ __forceinline__ void xcd_barrier(const XcdBarrier& b) {
;     asm volatile("s_waitcnt vmcnt(0)" ::: "memory");
;     __syncthreads();
;     if (threadIdx.x == 0) {
;         unsigned* bar = b.bar;
;         __builtin_amdgcn_s_waitcnt(0);
;         unsigned nloc = b.st[0], nx = b.st[1];
;         if (nloc == 0u) { xcd_barrier_complete(bar, b.x, nloc, nx); b.st[0] = nloc; b.st[1] = nx; }
;         const unsigned old = xb_add(&bar[XB_XSUB(b.x)], 1u);
.LBB0_1245:
	s_add_i32 s0, s86, 1
	s_cmp_ge_i32 s0, s27
	s_cbranch_scc1 .LBB0_1299
	s_waitcnt vmcnt(0)
	s_waitcnt lgkmcnt(0)
	s_barrier
	s_mov_b64 s[0:1], exec
	v_readlane_b32 s8, v252, 32
	v_readlane_b32 s9, v252, 33
	v_readlane_b32 s44, v252, 46
	s_and_b64 s[8:9], s[0:1], s[8:9]
	v_readlane_b32 s45, v252, 47
	s_mov_b64 exec, s[8:9]
	s_cbranch_execz .LBB0_1298
	v_mov_b32_e32 v0, 0x23fc8
	ds_read_b32 v1, v0
	s_waitcnt lgkmcnt(0)
	v_readfirstlane_b32 s40, v1
	s_cmp_eq_u32 s40, 1
	s_cbranch_scc0 .Lgb_orig_pool
	s_and_b32 s40, s2, 7
	s_lshl_b32 s40, s40, 7
	s_add_u32 s38, s24, 0x313800
	s_addc_u32 s39, s25, 0
	v_mov_b32_e32 v0, s40
	v_mov_b32_e32 v1, 1
	global_atomic_add v2, v0, v1, s[38:39] sc0
	s_mov_b32 s40, 0
	s_waitcnt vmcnt(0)
	v_or_b32_e32 v2, 31, v2
	v_add_u32_e32 v2, 1, v2

; __device__ __forceinline__ int opaque_tid() { int t = threadIdx.x; asm volatile("" : "+v"(t)); return t; }
; #define LAS __attribute__((address_space(3)))
; __device__ __forceinline__ void attn_phase(LAS unsigned char* lds, const bf16_t* QKV, const float* kmean, const float* biasT, bf16_t* O, int G, int wg) {
;     const int tid = opaque_tid(), lane = tid & 63, wid = tid >> 6, fr = lane & 15, fq = lane >> 4;
;     constexpr int KS_OFF = 0, VT_OFF = 64 * 256, VT_STR = 136, STAGE = VT_OFF + 128 * 144, BT_OFF = 3 * STAGE;
;     const int LK0 = fr * 256 + ((fq ^ (fr & 3)) << 4) + ((fr >> 2) << 6);
;     LAS float* BT = (LAS float*)(lds + BT_OFF);
;     for (int u = wg; u < 1024; u += G) {
.LBB0_1305:
	s_andn2_b64 vcc, exec, s[0:1]
	s_cbranch_vccnz .LBB0_1390
	v_readlane_b32 s0, v253, 46
	v_readlane_b32 s1, v253, 47
	v_mov_b32_e32 v169, v210
	s_andn2_b64 vcc, exec, s[0:1]
	s_cbranch_vccnz .LBB0_1377
	s_waitcnt vmcnt(0)
	v_bfe_u32 v2, v169, 4, 2
	v_ashrrev_i32_e32 v6, 6, v169
	s_movk_i32 s0, 0x880
	s_waitcnt lgkmcnt(0)
	v_and_b32_e32 v1, 15, v169
	v_lshlrev_b32_e32 v148, 4, v6
	v_lshlrev_b32_e32 v8, 5, v6
	v_mul_lo_u32 v219, v6, s0
	v_cmp_gt_i32_e64 s[40:41], 4, v6
	v_and_b32_e32 v6, 16, v169
	v_lshlrev_b32_e32 v222, 2, v2
	v_or_b32_e32 v206, v8, v1
	v_or_b32_e32 v221, 31, v8
	v_add_u32_e32 v8, 12, v222
	v_cmp_eq_u32_e64 s[42:43], 0, v6
	v_ashrrev_i32_e32 v146, 3, v169
	v_and_b32_e32 v7, 7, v169
	v_and_b32_e32 v174, 48, v169
	v_cndmask_b32_e64 v6, v8, v222, s[42:43]
	v_readlane_b32 s0, v252, 36
	v_lshlrev_b32_e32 v0, 8, v1
	v_bitop3_b32 v3, v2, v169, 3 bitop3:0x78
	v_lshlrev_b32_e32 v4, 4, v169
	v_lshl_add_u64 v[150:151], s[14:15], 0, v[174:175]
	v_and_b32_e32 v9, 15, v146
	v_lshlrev_b32_e32 v10, 1, v7
	v_lshlrev_b32_e32 v174, 1, v6
	v_readlane_b32 s1, v252, 37
	v_and_b32_e32 v144, 63, v169
	v_lshl_or_b32 v3, v3, 4, v0
	v_and_b32_e32 v5, 0xc0, v4
	v_bitop3_b32 v9, v10, v9, 1 bitop3:0x36
	v_lshl_add_u64 v[152:153], s[0:1], 0, v[174:175]
	s_movk_i32 s0, 0x80
	v_lshlrev_b32_e32 v0, 4, v7
	v_lshlrev_b32_e32 v207, 3, v2
	v_bitop3_b32 v11, v10, v146, 15 bitop3:0x78
	v_lshlrev_b32_e32 v218, 4, v9
	v_add_u32_e32 v9, 0, v219
	v_lshlrev_b32_e32 v220, 1, v144
	v_mul_u32_u24_e32 v223, 0x88, v1
	v_bitop3_b32 v225, v3, s0, v5 bitop3:0x36
	s_movk_i32 s0, 0xc0
	v_lshlrev_b32_e32 v174, 5, v7
	v_or_b32_e32 v183, v3, v5
	v_ashrrev_i32_e32 v147, 31, v146
	v_ashrrev_i32_e32 v149, 31, v148
	v_lshlrev_b32_e32 v208, 8, v146
	v_lshlrev_b32_e32 v217, 4, v11
	v_bitop3_b32 v224, v3, 64, v5 bitop3:0x36
	v_bitop3_b32 v226, v3, s0, v4 bitop3:0x34
	v_or_b32_e32 v154, 16, v222
	v_or_b32_e32 v145, 19, v222
	v_or_b32_e32 v156, 18, v222
	v_or_b32_e32 v155, 33, v222
	v_or_b32_e32 v158, 32, v222
	v_or_b32_e32 v157, 35, v222
	v_or_b32_e32 v160, 34, v222
	v_or_b32_e32 v159, 49, v222
	v_or_b32_e32 v162, 48, v222
	v_or_b32_e32 v161, 51, v222
	v_or_b32_e32 v164, 50, v222
	v_lshl_add_u64 v[166:167], s[14:15], 0, v[174:175]
	v_add3_u32 v168, 0, v207, v223
	v_lshl_add_u32 v227, v2, 5, 0
	v_add_u32_e32 v228, v9, v220
	v_lshlrev_b32_e32 v174, 1, v0
	s_and_b32 s52, s2, 7
	s_lshl_b32 s52, s52, 4
	s_bfe_u32 s53, s2, 0x40003
	s_and_b32 s9, s2, 0x380
	s_or_b32 s9, s9, s52
	s_or_b32 s9, s9, s53
	s_and_b32 s52, s28, 0x7f
	s_cmp_eq_u32 s52, 0
	s_cselect_b32 s9, s9, s2
	s_mov_b32 s52, s9
	s_mov_b32 s53, s9
	s_branch .LBB0_1309

; __device__ __forceinline__ unsigned xb_add(unsigned* p, unsigned v) { return __hip_atomic_fetch_add(p, v, __ATOMIC_RELAXED, __HIP_MEMORY_SCOPE_AGENT); }
; __device__ __forceinline__ void xcd_barrier(const XcdBarrier& b) {
;     asm volatile("s_waitcnt vmcnt(0)" ::: "memory");
;     __syncthreads();
;     if (threadIdx.x == 0) {
;         unsigned* bar = b.bar;
;         __builtin_amdgcn_s_waitcnt(0);
;         unsigned nloc = b.st[0], nx = b.st[1];
;         if (nloc == 0u) { xcd_barrier_complete(bar, b.x, nloc, nx); b.st[0] = nloc; b.st[1] = nx; }
;         const unsigned old = xb_add(&bar[XB_XSUB(b.x)], 1u);
.LBB0_1377:
	s_add_i32 s66, s86, 2
	s_cmp_ge_i32 s66, s27
	s_cbranch_scc1 .LBB0_1389
	s_waitcnt vmcnt(0)
	s_waitcnt lgkmcnt(0)
	s_barrier
	s_mov_b64 s[0:1], exec
	v_readlane_b32 s38, v252, 32
	v_readlane_b32 s39, v252, 33
	v_readlane_b32 s46, v252, 46
	s_and_b64 s[38:39], s[0:1], s[38:39]
	v_readlane_b32 s47, v252, 47
	s_mov_b64 exec, s[38:39]
	s_cbranch_execz .LBB0_1617
	v_mov_b32_e32 v0, 0x23fc8
	ds_read_b32 v1, v0
	s_waitcnt lgkmcnt(0)
	v_readfirstlane_b32 s40, v1
	s_cmp_eq_u32 s40, 1
	s_cbranch_scc0 .Lgb_orig_attn
	s_and_b32 s40, s2, 7
	s_lshl_b32 s40, s40, 7
	s_add_u32 s38, s24, 0x313800
	s_addc_u32 s39, s25, 0
	v_mov_b32_e32 v0, s40
	v_mov_b32_e32 v1, 1
	global_atomic_add v2, v0, v1, s[38:39] sc0
	s_mov_b32 s40, 0
	s_waitcnt vmcnt(0)
	v_or_b32_e32 v2, 31, v2
	v_add_u32_e32 v2, 1, v2

; __device__ __forceinline__ void xcd_barrier(const XcdBarrier& b) {
;     ...
;     if (threadIdx.x == 0) {
;         unsigned* bar = b.bar;
;         __builtin_amdgcn_s_waitcnt(0);
;         unsigned nloc = b.st[0], nx = b.st[1];
;         if (nloc == 0u) { xcd_barrier_complete(bar, b.x, nloc, nx); b.st[0] = nloc; b.st[1] = nx; }
.Lgb_orig_attn:
	v_readlane_b32 s9, v254, 56
	s_waitcnt vmcnt(0) expcnt(0) lgkmcnt(0)
	s_nop 0
	v_mov_b32_e32 v0, s9
	ds_read_b32 v2, v0
	v_readlane_b32 s9, v254, 57
	s_waitcnt lgkmcnt(0)
	v_cmp_ne_u32_e32 vcc, 0, v2
	v_mov_b32_e32 v0, s9
	ds_read_b32 v0, v0
	s_cbranch_vccnz .LBB0_1573
	s_mov_b32 s9, 1
	s_branch .LBB0_1382

; __device__ __forceinline__ int opaque_tid() { int t = threadIdx.x; asm volatile("" : "+v"(t)); return t; }
; __device__ __forceinline__ void gla_phase(LAS unsigned char* lds, const bf16_t* P, const float* hn, bf16_t* O, int G, int wg) {
;     const int tid = opaque_tid(), lane = tid & 63, wid = tid >> 6, fr = lane & 15, fq = lane >> 4;
;     constexpr int QT = 0, KT = 16384, ST = 32768, KTT = 65536, VT = 81920, AM = 98304, PART = 106496, SSQX = 110592, HNL = 111104;
;     const int LK0 = fr * 256 + ((fq ^ (fr & 3)) << 4) + ((fr >> 2) << 6);
;     const int LS0 = fr * 128 + ((fq ^ ((fr >> 1) & 3)) << 4) + ((fr >> 3) << 6);
;     constexpr float LOG2E = 1.4426950408889634f;
;     const int dp = tid & 63, tq = tid >> 6;
;     const int tt = wid & 3, eh = wid >> 2;
;     ...
;     for (int unit = wg; unit < NB * NH; unit += G) {
;         const int b = unit >> 3, h = unit & 7;
.LBB0_1393:
	s_andn2_b64 vcc, exec, s[0:1]
	s_cbranch_vccnz .LBB0_1618
	v_readlane_b32 s0, v255, 12
	s_cmp_eq_u32 s0, 0
	v_readlane_b32 s0, v255, 10
	s_cselect_b64 s[38:39], -1, 0
	v_readlane_b32 s1, v255, 11
	v_readlane_b32 s8, v253, 48
	s_or_b64 s[0:1], s[38:39], s[0:1]
	v_readlane_b32 s9, v253, 49
	s_and_b64 s[8:9], s[0:1], s[8:9]
	s_mov_b64 s[0:1], -1
	s_and_b64 vcc, exec, s[8:9]
	s_cbranch_vccnz .LBB0_1416
	v_readlane_b32 s0, v253, 50
	v_readlane_b32 s1, v253, 51
	v_readlane_b32 s80, v252, 36
	v_mov_b32_e32 v0, v210
	s_and_b64 vcc, exec, s[0:1]
	v_readlane_b32 s81, v252, 37
	s_cbranch_vccz .LBB0_1520
	v_readlane_b32 s0, v255, 10
	v_readlane_b32 s1, v255, 11
	v_and_b32_e32 v7, 15, v0
	v_bfe_u32 v10, v0, 1, 3
	v_bfe_u32 v4, v0, 4, 2
	s_and_b64 s[0:1], s[0:1], exec
	v_readlane_b32 s40, v252, 0
	s_waitcnt vmcnt(0)
	v_ashrrev_i32_e32 v3, 6, v0
	s_waitcnt lgkmcnt(0)
	v_bitop3_b32 v1, v10, v4, 3 bitop3:0x6c
	v_lshlrev_b32_e32 v2, 7, v7
	s_cselect_b32 s0, 0x200, 0
	v_readlane_b32 s52, v252, 12
	v_and_b32_e32 v5, 3, v3
	v_lshl_or_b32 v12, v1, 4, v2
	v_bitop3_b32 v1, v4, v0, 3 bitop3:0x78
	v_lshlrev_b32_e32 v22, 1, v3
	v_bfe_u32 v23, v0, 5, 1
	v_readlane_b32 s53, v252, 13
	s_add_u32 s0, s52, s0
	v_and_or_b32 v1, v0, 12, v1
	v_lshlrev_b32_e32 v15, 8, v7
	v_bitop3_b32 v22, v22, v7, v23 bitop3:0x36
	v_lshrrev_b32_e32 v24, 1, v0
	v_lshlrev_b32_e32 v29, 1, v5
	v_readlane_b32 s41, v252, 1
	s_addc_u32 s1, s53, 0
	v_lshlrev_b32_e32 v14, 4, v1
	s_movk_i32 s16, 0x80
	v_lshlrev_b32_e32 v17, 2, v0
	v_readlane_b32 s8, v254, 59
	v_ashrrev_i32_e32 v1, 31, v0
	v_lshlrev_b32_e32 v82, 3, v3
	v_add_u32_e32 v21, 0, v15
	v_lshlrev_b32_e32 v22, 4, v22
	v_and_b32_e32 v24, 8, v24
	v_bitop3_b32 v10, v29, v10, v23 bitop3:0x36
	v_readlane_b32 s44, v252, 4
	v_readlane_b32 s45, v252, 5
	v_readlane_b32 s46, v252, 6
	v_readlane_b32 s47, v252, 7
	v_readlane_b32 s48, v252, 8
	v_readlane_b32 s49, v252, 9
	v_readlane_b32 s50, v252, 10
	v_readlane_b32 s51, v252, 11
	v_readlane_b32 s54, v252, 14
	v_readlane_b32 s55, v252, 15
	v_and_b32_e32 v11, 63, v0
	v_lshlrev_b32_e32 v13, 3, v0
	v_ashrrev_i32_e32 v16, 8, v0
	v_cmp_gt_i32_e64 s[40:41], s16, v0
	v_add_u32_e32 v145, s8, v17
	v_lshl_add_u64 v[80:81], v[0:1], 2, s[0:1]
	v_ashrrev_i32_e32 v83, 31, v82
	s_add_i32 s8, 0, 0x1a000
	s_add_i32 s0, 0, 0x1b000
	v_and_b32_e32 v147, 0xffffff30, v0
	v_and_b32_e32 v6, 16, v0
	v_and_b32_e32 v19, 0xffffffc0, v0
	v_and_b32_e32 v20, 48, v0
	v_add3_u32 v149, v21, v22, v24
	v_bfe_u32 v21, v0, 2, 4
	v_bitop3_b32 v25, v3, v0, 7 bitop3:0x78
	v_lshlrev_b32_e32 v10, 4, v10
	s_add_i32 s1, 0, 0x18000
	v_and_b32_e32 v0, 0xffffff00, v0
	v_lshlrev_b32_e32 v2, 1, v11
	v_lshlrev_b64 v[84:85], 13, v[82:83]
	v_lshlrev_b32_e32 v83, 3, v11
	v_lshl_add_u32 v1, v3, 9, s8
	v_lshlrev_b32_e32 v22, 8, v11
	v_add3_u32 v10, s1, v10, v24
	v_lshlrev_b32_e32 v23, 11, v3
	v_cmp_gt_u32_e64 s[44:45], 16, v11
	v_add_u32_e32 v0, s0, v0
	v_lshlrev_b32_e32 v11, 6, v5
	v_lshlrev_b32_e32 v24, 2, v7
	v_cmp_lt_i32_e64 s[46:47], 0, v3
	v_cmp_lt_i32_e64 s[48:49], 1, v3
	v_cmp_lt_i32_e64 s[50:51], 2, v3
	v_cmp_lt_i32_e64 s[52:53], 3, v3
	v_cmp_lt_i32_e64 s[54:55], 4, v3
	v_cmp_lt_i32_e64 s[56:57], 5, v3
	v_cmp_lt_i32_e64 s[58:59], 6, v3
	v_bitop3_b32 v3, v82, v21, 8 bitop3:0x6c
	v_and_b32_e32 v17, 12, v17
	s_add_i32 s9, 0, 0x10000
	v_add3_u32 v156, v0, v11, v24
	v_lshlrev_b32_e32 v3, 4, v3
	v_or_b32_e32 v11, 1, v82
	v_add_u32_e32 v155, s9, v23
	v_or3_b32 v3, v3, v23, v17
	v_lshlrev_b32_e32 v23, 8, v11
	v_bitop3_b32 v11, v11, v21, 9 bitop3:0x6c
	v_lshlrev_b32_e32 v11, 4, v11
	v_or3_b32 v11, v11, v23, v17
	v_or_b32_e32 v23, 2, v82
	v_lshlrev_b32_e32 v24, 8, v23
	v_bitop3_b32 v23, v23, v21, 10 bitop3:0x6c
	v_lshlrev_b32_e32 v23, 4, v23
	v_or3_b32 v23, v23, v24, v17
	v_or_b32_e32 v24, 3, v82
	v_lshlrev_b32_e32 v29, 8, v24
	v_bitop3_b32 v24, v24, v21, 11 bitop3:0x6c
	v_lshlrev_b32_e32 v24, 4, v24
	v_or3_b32 v24, v24, v29, v17
	v_or_b32_e32 v29, 4, v82
	v_lshlrev_b32_e32 v30, 8, v29
	v_bitop3_b32 v29, v29, v21, 12 bitop3:0x6c
	v_lshlrev_b32_e32 v29, 4, v29
	v_or3_b32 v29, v29, v30, v17
	v_or_b32_e32 v30, 5, v82
	v_lshlrev_b32_e32 v31, 8, v30
	v_bitop3_b32 v30, v30, v21, 13 bitop3:0x6c
	v_lshlrev_b32_e32 v30, 4, v30
	v_lshlrev_b32_e32 v18, 4, v5
	v_or3_b32 v30, v30, v31, v17
	v_or_b32_e32 v31, 6, v82
	v_or_b32_e32 v86, v18, v7
	v_lshlrev_b32_e32 v32, 8, v31
	v_bitop3_b32 v31, v31, v21, 14 bitop3:0x6c
	v_readlane_b32 s42, v252, 2
	v_readlane_b32 s43, v252, 3
	v_lshl_add_u32 v146, v86, 2, s0
	v_lshlrev_b32_e32 v4, 2, v4
	v_lshl_add_u32 v22, v25, 4, v22
	v_lshlrev_b32_e32 v25, 1, v16
	v_lshlrev_b32_e32 v31, 4, v31
	s_movk_i32 s0, 0xc0
	v_or_b32_e32 v144, v14, v15
	v_add_u32_e32 v8, 12, v4
	v_cmp_eq_u32_e64 s[42:43], 0, v6
	v_or_b32_e32 v18, v18, v4
	v_or3_b32 v31, v31, v32, v17
	v_or_b32_e32 v32, 7, v82
	v_bitop3_b32 v157, v14, 64, v15 bitop3:0x36
	v_bitop3_b32 v158, v14, s16, v15 bitop3:0x36
	v_bitop3_b32 v159, v14, s0, v15 bitop3:0x36
	v_or_b32_e32 v14, 1, v25
	v_cndmask_b32_e64 v6, v8, v4, s[42:43]
	v_lshl_add_u32 v150, v5, 12, 0
	v_or_b32_e32 v27, 2, v18
	v_or_b32_e32 v28, 3, v18
	v_lshl_add_u32 v153, v5, 11, s1
	v_bitop3_b32 v21, v32, v21, 15 bitop3:0x6c
	v_cmp_ge_i32_e64 s[60:61], v25, v5
	v_cmp_ge_i32_e64 s[62:63], v14, v5
	v_lshl_or_b32 v5, v16, 5, v7
	v_and_or_b32 v87, v13, 64, v12
	v_lshlrev_b32_e32 v88, 6, v16
	v_lshlrev_b32_e32 v174, 1, v6
	v_lshlrev_b32_e32 v148, 14, v16
	v_lshlrev_b32_e32 v26, 13, v16
	s_add_i32 s1, 0, 0x14000
	v_lshlrev_b32_e32 v33, 8, v32
	v_lshlrev_b32_e32 v21, 4, v21
	v_cmp_lt_i32_e64 s[64:65], v5, v18
	v_cmp_gt_i32_e64 s[66:67], v5, v18
	v_cmp_lt_i32_e64 s[68:69], v5, v27
	v_cmp_lt_i32_e64 s[70:71], v5, v28
	v_lshlrev_b32_e32 v7, 7, v5
	v_or_b32_e32 v5, 16, v5
	v_bitop3_b32 v160, v12, 64, v13 bitop3:0x34
	v_lshl_add_u64 v[8:9], s[80:81], 0, v[174:175]
	v_add_u32_e32 v20, s8, v20
	v_ashrrev_i32_e32 v89, 31, v88
	v_xor_b32_e32 v0, 0x4000, v148
	v_or3_b32 v17, v21, v33, v17
	v_cmp_lt_i32_e64 s[72:73], v5, v18
	v_cmp_gt_i32_e64 s[74:75], v5, v18
	v_cmp_lt_i32_e64 s[76:77], v5, v27
	v_cmp_lt_i32_e64 s[78:79], v5, v28
	v_lshlrev_b32_e32 v5, 7, v5
	v_xor_b32_e32 v12, 0x2000, v26
	v_add_u32_e32 v13, s1, v87
	v_add_u32_e32 v14, s1, v160
	v_add_u32_e32 v151, 0, v26
	v_add_u32_e32 v152, 0, v148
	v_add_u32_e32 v154, s1, v26
	v_lshl_add_u64 v[90:91], v[88:89], 1, v[8:9]
	v_lshlrev_b32_e32 v92, 1, v2
	v_add_u32_e32 v161, v1, v83
	v_lshlrev_b32_e32 v94, 1, v4
	v_add_u32_e32 v162, v149, v0
	v_add_u32_e32 v163, 0, v3
	v_add_u32_e32 v164, 0, v11
	v_add_u32_e32 v165, 0, v23
	v_add_u32_e32 v166, 0, v24
	v_add_u32_e32 v167, 0, v29
	v_add_u32_e32 v168, 0, v30
	v_add_u32_e32 v169, 0, v31
	v_add_u32_e32 v170, 0, v17
	v_add_u32_e32 v171, 0, v22
	v_add_u32_e32 v180, v10, v7
	v_add_u32_e32 v181, v10, v5
	v_add_u32_e32 v182, v13, v12
	v_add_u32_e32 v183, v14, v12
	v_lshlrev_b32_e32 v96, 1, v6
	v_add_u32_e32 v184, v20, v19
	s_and_b32 s9, s2, 7
	s_lshl_b32 s9, s9, 4
	s_lshr_b32 s0, s2, 3
	s_or_b32 s9, s9, s0
	s_and_b32 s0, s28, 0x7f
	s_cmp_eq_u32 s0, 0
	s_cselect_b32 s9, s9, s2
	s_branch .LBB0_1398

; __device__ __forceinline__ unsigned xb_add(unsigned* p, unsigned v) { return __hip_atomic_fetch_add(p, v, __ATOMIC_RELAXED, __HIP_MEMORY_SCOPE_AGENT); }
; __device__ __forceinline__ void xcd_barrier(const XcdBarrier& b) {
;     asm volatile("s_waitcnt vmcnt(0)" ::: "memory");
;     __syncthreads();
;     if (threadIdx.x == 0) {
;         unsigned* bar = b.bar;
;         __builtin_amdgcn_s_waitcnt(0);
;         unsigned nloc = b.st[0], nx = b.st[1];
;         if (nloc == 0u) { xcd_barrier_complete(bar, b.x, nloc, nx); b.st[0] = nloc; b.st[1] = nx; }
;         const unsigned old = xb_add(&bar[XB_XSUB(b.x)], 1u);
.LBB0_1672:
	s_add_i32 s8, s66, 1
	s_cmp_ge_i32 s8, s27
	s_cbranch_scc1 .LBB0_1684
	s_waitcnt vmcnt(0)
	s_waitcnt lgkmcnt(0)
	s_barrier
	s_mov_b64 s[0:1], exec
	v_readlane_b32 s38, v252, 32
	v_readlane_b32 s39, v252, 33
	v_readlane_b32 s46, v252, 46
	s_and_b64 s[38:39], s[0:1], s[38:39]
	v_readlane_b32 s47, v252, 47
	s_mov_b64 exec, s[38:39]
	s_cbranch_execz .LBB0_1727
	v_mov_b32_e32 v0, 0x23fc8
	ds_read_b32 v1, v0
	s_waitcnt lgkmcnt(0)
	v_readfirstlane_b32 s40, v1
	s_cmp_eq_u32 s40, 1
	s_cbranch_scc0 .Lgb_orig_g2
	s_and_b32 s40, s2, 7
	s_lshl_b32 s40, s40, 7
	s_add_u32 s38, s24, 0x313800
	s_addc_u32 s39, s25, 0
	v_mov_b32_e32 v0, s40
	v_mov_b32_e32 v1, 1
	global_atomic_add v2, v0, v1, s[38:39] sc0
	s_mov_b32 s40, 0
	s_waitcnt vmcnt(0)
	v_or_b32_e32 v2, 31, v2
	v_add_u32_e32 v2, 1, v2

; __device__ __forceinline__ unsigned xb_add(unsigned* p, unsigned v) { return __hip_atomic_fetch_add(p, v, __ATOMIC_RELAXED, __HIP_MEMORY_SCOPE_AGENT); }
; __device__ __forceinline__ void xcd_barrier(const XcdBarrier& b) {
;     asm volatile("s_waitcnt vmcnt(0)" ::: "memory");
;     __syncthreads();
;     if (threadIdx.x == 0) {
;         unsigned* bar = b.bar;
;         __builtin_amdgcn_s_waitcnt(0);
;         unsigned nloc = b.st[0], nx = b.st[1];
;         if (nloc == 0u) { xcd_barrier_complete(bar, b.x, nloc, nx); b.st[0] = nloc; b.st[1] = nx; }
;         const unsigned old = xb_add(&bar[XB_XSUB(b.x)], 1u);
.LBB0_1775:
	s_add_i32 s8, s66, 2
	s_cmp_ge_i32 s8, s27
	s_cbranch_scc1 .LBB0_1829
	s_waitcnt vmcnt(0)
	s_waitcnt vmcnt(0) lgkmcnt(0)
	s_barrier
	s_mov_b64 s[0:1], exec
	v_readlane_b32 s38, v252, 32
	v_readlane_b32 s39, v252, 33
	s_and_b64 s[38:39], s[0:1], s[38:39]
	s_mov_b64 exec, s[38:39]
	s_cbranch_execz .LBB0_1828
	v_mov_b32_e32 v0, 0x23fc8
	ds_read_b32 v1, v0
	s_waitcnt lgkmcnt(0)
	v_readfirstlane_b32 s40, v1
	s_cmp_eq_u32 s40, 1
	s_cbranch_scc0 .Lgb_orig_g3
	s_and_b32 s40, s2, 7
	s_lshl_b32 s40, s40, 7
	s_add_u32 s38, s24, 0x313800
	s_addc_u32 s39, s25, 0
	v_mov_b32_e32 v0, s40
	v_mov_b32_e32 v1, 1
	global_atomic_add v2, v0, v1, s[38:39] sc0
	s_mov_b32 s40, 0
	s_waitcnt vmcnt(0)
	v_or_b32_e32 v2, 31, v2
	v_add_u32_e32 v2, 1, v2

; __device__ __forceinline__ unsigned xb_add(unsigned* p, unsigned v) { return __hip_atomic_fetch_add(p, v, __ATOMIC_RELAXED, __HIP_MEMORY_SCOPE_AGENT); }
; __device__ __forceinline__ void xcd_barrier(const XcdBarrier& b) {
;     asm volatile("s_waitcnt vmcnt(0)" ::: "memory");
;     __syncthreads();
;     if (threadIdx.x == 0) {
;         unsigned* bar = b.bar;
;         __builtin_amdgcn_s_waitcnt(0);
;         unsigned nloc = b.st[0], nx = b.st[1];
;         if (nloc == 0u) { xcd_barrier_complete(bar, b.x, nloc, nx); b.st[0] = nloc; b.st[1] = nx; }
;         const unsigned old = xb_add(&bar[XB_XSUB(b.x)], 1u);
.LBB0_1868:
	s_add_i32 s0, s66, 3
	s_mov_b32 s86, s0
	s_cmp_ge_i32 s0, s27
	s_cbranch_scc1 .LBB0_1922
	s_waitcnt vmcnt(0)
	s_waitcnt vmcnt(0) lgkmcnt(0)
	s_barrier
	s_mov_b64 s[0:1], exec
	v_readlane_b32 s8, v252, 32
	v_readlane_b32 s9, v252, 33
	s_and_b64 s[8:9], s[0:1], s[8:9]
	s_mov_b64 exec, s[8:9]
	s_cbranch_execz .LBB0_1921
	s_cmp_eq_u32 s86, 20
	s_cbranch_scc1 .Lgb_orig_g4
	v_mov_b32_e32 v0, 0x23fc8
	ds_read_b32 v1, v0
	s_waitcnt lgkmcnt(0)
	v_readfirstlane_b32 s40, v1
	s_cmp_eq_u32 s40, 1
	s_cbranch_scc0 .Lgb_orig_g4
	s_and_b32 s40, s2, 7
	s_lshl_b32 s40, s40, 7
	s_add_u32 s38, s24, 0x313800
	s_addc_u32 s39, s25, 0
	v_mov_b32_e32 v0, s40
	v_mov_b32_e32 v1, 1
	global_atomic_add v2, v0, v1, s[38:39] sc0
	s_mov_b32 s40, 0
	s_waitcnt vmcnt(0)
	v_or_b32_e32 v2, 31, v2
	v_add_u32_e32 v2, 1, v2
